# T21 store widening: dil band item epilogue 16x global_store_dwordx2 -> 8x dwordx4 via v_permlane32_swap_b32 pairs
# speedup vs baseline: 1.0111x; 1.0038x over previous
; #define LAS __attribute__((address_space(3)))
; __device__ __forceinline__ unsigned pk_bf16(float lo, float hi) { const f32x2 v = {lo, hi}; const bf16v2 b = __builtin_convertvector(v, bf16v2); return __builtin_bit_cast(unsigned, b); }
; __device__ __forceinline__ float xsum32(float v) { const auto r = __builtin_amdgcn_permlane32_swap(__float_as_uint(v), __float_as_uint(v), false, false); return __uint_as_float(r[0]) + __uint_as_float(r[1]); }
; template <int HD, int DV, int HW, int MODE> ...
;     ...
;     const float lt = xsum32(l), inv = 1.0f / lt;
;     const size_t tok = tok0 + (size_t)r * (iw + ql);
;     if (MODE == 0) {
;         if (hh == 0) lsep[tok * 8] = m + __builtin_amdgcn_logf(lt);
; #pragma unroll
;         for (int t = 0; t < NTV; ++t)
; #pragma unroll
;             for (int i4 = 0; i4 < 4; ++i4) { u32x2 wv; wv.x = pk_bf16(O[t][4 * i4] * inv, O[t][4 * i4 + 1] * inv); wv.y = pk_bf16(O[t][4 * i4 + 2] * inv, O[t][4 * i4 + 3] * inv);
;                 *(u32x2*)(op + tok * old + 32 * t + 8 * i4 + 4 * hh) = wv; }
;     ...
;     __syncthreads();
; }
; __device__ __forceinline__ void dil_attn_phase(const Params& p, int half, LAS unsigned char* lds) {
;     const bf16_t* PROJ = (const bf16_t*)(p.ws + WS_PROJ); bf16_t* OG = (bf16_t*)(p.ws + WS_OG); float* LSE = (float*)(p.ws + WS_LSE);
;     (void)half;
;     for (int it = blockIdx.x; it < 1536; it += gridDim.x) {
.LBB0_83:
	s_or_b64 exec, exec, s[40:41]
	v_div_scale_f32 v2, s[4:5], v1, v1, 1.0
	v_rcp_f32_e32 v3, v2
	v_div_scale_f32 v4, vcc, 1.0, v1, 1.0
	s_lshl_b64 s[4:5], s[26:27], 25
	v_fma_f32 v5, -v2, v3, 1.0
	v_fmac_f32_e32 v3, v5, v3
	v_mul_f32_e32 v5, v4, v3
	v_fma_f32 v6, -v2, v5, v4
	v_fmac_f32_e32 v5, v6, v3
	s_add_u32 s2, s90, s4
	v_fma_f32 v2, -v2, v5, v4
	s_addc_u32 s5, s91, s5
	v_div_fmas_f32 v2, v2, v3, v5
	s_add_u32 s4, s2, s22
	v_div_fixup_f32 v2, v2, v1, 1.0
	s_addc_u32 s5, s5, 0
	v_lshlrev_b64 v[4:5], 11, v[160:161]
	v_lshl_add_u64 v[4:5], s[4:5], 0, v[4:5]
	v_mov_b32_e32 v163, v0
	v_lshl_add_u64 v[4:5], v[4:5], 0, v[162:163]
	v_bfe_u32 v136, v207, 5, 1
	v_lshlrev_b32_e32 v136, 3, v136
	v_mov_b32_e32 v137, v0
	v_lshl_add_u64 v[4:5], v[4:5], 0, v[136:137]
	v_pk_mul_f32 v[6:7], v[64:65], v[2:3] op_sel_hi:[1,0]
	v_pk_mul_f32 v[8:9], v[66:67], v[2:3] op_sel_hi:[1,0]
	v_cvt_pk_bf16_f32 v128, v6, v7
	v_cvt_pk_bf16_f32 v129, v8, v9
	v_pk_mul_f32 v[6:7], v[68:69], v[2:3] op_sel_hi:[1,0]
	v_pk_mul_f32 v[8:9], v[70:71], v[2:3] op_sel_hi:[1,0]
	v_cvt_pk_bf16_f32 v130, v6, v7
	v_cvt_pk_bf16_f32 v131, v8, v9
	s_nop 1
	v_permlane32_swap_b32_e32 v128, v130
	v_permlane32_swap_b32_e32 v129, v131
	global_store_dwordx4 v[4:5], v[128:131], off
	v_pk_mul_f32 v[6:7], v[72:73], v[2:3] op_sel_hi:[1,0]
	v_pk_mul_f32 v[8:9], v[74:75], v[2:3] op_sel_hi:[1,0]
	v_cvt_pk_bf16_f32 v132, v6, v7
	v_cvt_pk_bf16_f32 v133, v8, v9
	v_pk_mul_f32 v[6:7], v[76:77], v[2:3] op_sel_hi:[1,0]
	v_pk_mul_f32 v[8:9], v[78:79], v[2:3] op_sel_hi:[1,0]
	v_cvt_pk_bf16_f32 v134, v6, v7
	v_cvt_pk_bf16_f32 v135, v8, v9
	s_nop 1
	v_permlane32_swap_b32_e32 v132, v134
	v_permlane32_swap_b32_e32 v133, v135
	global_store_dwordx4 v[4:5], v[132:135], off offset:32
	v_pk_mul_f32 v[6:7], v[48:49], v[2:3] op_sel_hi:[1,0]
	v_pk_mul_f32 v[8:9], v[50:51], v[2:3] op_sel_hi:[1,0]
	v_cvt_pk_bf16_f32 v128, v6, v7
	v_cvt_pk_bf16_f32 v129, v8, v9
	v_pk_mul_f32 v[6:7], v[52:53], v[2:3] op_sel_hi:[1,0]
	v_pk_mul_f32 v[8:9], v[54:55], v[2:3] op_sel_hi:[1,0]
	v_cvt_pk_bf16_f32 v130, v6, v7
	v_cvt_pk_bf16_f32 v131, v8, v9
	s_nop 1
	v_permlane32_swap_b32_e32 v128, v130
	v_permlane32_swap_b32_e32 v129, v131
	global_store_dwordx4 v[4:5], v[128:131], off offset:64
	v_pk_mul_f32 v[6:7], v[56:57], v[2:3] op_sel_hi:[1,0]
	v_pk_mul_f32 v[8:9], v[58:59], v[2:3] op_sel_hi:[1,0]
	v_cvt_pk_bf16_f32 v132, v6, v7
	v_cvt_pk_bf16_f32 v133, v8, v9
	v_pk_mul_f32 v[6:7], v[60:61], v[2:3] op_sel_hi:[1,0]
	v_pk_mul_f32 v[8:9], v[62:63], v[2:3] op_sel_hi:[1,0]
	v_cvt_pk_bf16_f32 v134, v6, v7
	v_cvt_pk_bf16_f32 v135, v8, v9
	s_nop 1
	v_permlane32_swap_b32_e32 v132, v134
	v_permlane32_swap_b32_e32 v133, v135
	global_store_dwordx4 v[4:5], v[132:135], off offset:96
	v_pk_mul_f32 v[6:7], v[32:33], v[2:3] op_sel_hi:[1,0]
	v_pk_mul_f32 v[8:9], v[34:35], v[2:3] op_sel_hi:[1,0]
	v_cvt_pk_bf16_f32 v128, v6, v7
	v_cvt_pk_bf16_f32 v129, v8, v9
	v_pk_mul_f32 v[6:7], v[36:37], v[2:3] op_sel_hi:[1,0]
	v_pk_mul_f32 v[8:9], v[38:39], v[2:3] op_sel_hi:[1,0]
	v_cvt_pk_bf16_f32 v130, v6, v7
	v_cvt_pk_bf16_f32 v131, v8, v9
	s_nop 1
	v_permlane32_swap_b32_e32 v128, v130
	v_permlane32_swap_b32_e32 v129, v131
	global_store_dwordx4 v[4:5], v[128:131], off offset:128
	v_pk_mul_f32 v[6:7], v[40:41], v[2:3] op_sel_hi:[1,0]
	v_pk_mul_f32 v[8:9], v[42:43], v[2:3] op_sel_hi:[1,0]
	v_cvt_pk_bf16_f32 v132, v6, v7
	v_cvt_pk_bf16_f32 v133, v8, v9
	v_pk_mul_f32 v[6:7], v[44:45], v[2:3] op_sel_hi:[1,0]
	v_pk_mul_f32 v[8:9], v[46:47], v[2:3] op_sel_hi:[1,0]
	v_cvt_pk_bf16_f32 v134, v6, v7
	v_cvt_pk_bf16_f32 v135, v8, v9
	s_nop 1
	v_permlane32_swap_b32_e32 v132, v134
	v_permlane32_swap_b32_e32 v133, v135
	global_store_dwordx4 v[4:5], v[132:135], off offset:160
	v_pk_mul_f32 v[6:7], v[16:17], v[2:3] op_sel_hi:[1,0]
	v_pk_mul_f32 v[8:9], v[18:19], v[2:3] op_sel_hi:[1,0]
	v_cvt_pk_bf16_f32 v128, v6, v7
	v_cvt_pk_bf16_f32 v129, v8, v9
	v_pk_mul_f32 v[6:7], v[20:21], v[2:3] op_sel_hi:[1,0]
	v_pk_mul_f32 v[8:9], v[22:23], v[2:3] op_sel_hi:[1,0]
	v_cvt_pk_bf16_f32 v130, v6, v7
	v_cvt_pk_bf16_f32 v131, v8, v9
	s_nop 1
	v_permlane32_swap_b32_e32 v128, v130
	v_permlane32_swap_b32_e32 v129, v131
	global_store_dwordx4 v[4:5], v[128:131], off offset:192
	v_pk_mul_f32 v[6:7], v[24:25], v[2:3] op_sel_hi:[1,0]
	v_pk_mul_f32 v[8:9], v[26:27], v[2:3] op_sel_hi:[1,0]
	v_cvt_pk_bf16_f32 v132, v6, v7
	v_cvt_pk_bf16_f32 v133, v8, v9
	v_pk_mul_f32 v[6:7], v[28:29], v[2:3] op_sel_hi:[1,0]
	v_pk_mul_f32 v[8:9], v[30:31], v[2:3] op_sel_hi:[1,0]
	v_cvt_pk_bf16_f32 v134, v6, v7
	v_cvt_pk_bf16_f32 v135, v8, v9
	s_nop 1
	v_permlane32_swap_b32_e32 v132, v134
	v_permlane32_swap_b32_e32 v133, v135
	global_store_dwordx4 v[4:5], v[132:135], off offset:224
	s_add_i32 s15, s15, s50
	s_cmpk_gt_i32 s15, 0x5ff
	s_barrier
	s_cbranch_scc1 .LBB0_73
